# dn_chain body rescheduled: counted waits, ds_read_b64 conflict-free fragment reads issued ahead, DN_OUT 16-wide + DPP, operand loads spread through the compute streams
# baseline (speedup 1.0000x reference)
.Lc_top_go:
	ds_write_b128 v148, v[26:29]
	ds_write_b128 v148, v[30:33] offset:9216
	ds_write_b128 v148, v[34:37] offset:18432
	ds_write_b128 v148, v[38:41] offset:27648
	ds_write_b128 v148, v[42:45] offset:36864
	s_cmp_lt_u32 s0, 30
	s_cselect_b64 s[20:21], -1, 0
	s_cmp_gt_u32 s0, 29
	v_readlane_b32 s6, v248, 44
	s_cselect_b64 s[18:19], -1, 0
	v_readlane_b32 s7, v248, 45
	s_and_b64 vcc, exec, s[18:19]
	v_lshl_add_u64 v[136:137], v[130:131], 0, s[6:7]
	v_readlane_b32 s6, v252, s0
	v_readlane_b32 s7, v253, s0
	s_nop 1
	v_mov_b32_e32 v134, s6
	v_mov_b32_e32 v0, s7
	s_waitcnt lgkmcnt(0)
	s_barrier
	s_cbranch_vccnz .Lc_skipA
	s_branch .LBB0_1013
	v_add_co_u32_e32 v26, vcc, 0x1ad10000, v136
	s_nop 0
	s_nop 0
	v_addc_co_u32_e32 v27, vcc, 0, v137, vcc
	v_add_co_u32_e32 v30, vcc, 0x1bd10000, v136
	s_nop 0
	s_nop 0
	v_addc_co_u32_e32 v31, vcc, 0, v137, vcc
	v_add_co_u32_e32 v34, vcc, 0x1cd10000, v136
	global_load_dwordx4 v[26:29], v[26:27], off
	s_nop 0
	global_load_dwordx4 v[30:33], v[30:31], off
	v_addc_co_u32_e32 v35, vcc, 0, v137, vcc
	v_add_co_u32_e32 v38, vcc, 0x1dd10000, v136
	s_nop 0
	s_nop 0
	v_addc_co_u32_e32 v39, vcc, 0, v137, vcc
	v_add_co_u32_e32 v42, vcc, 0x13910000, v136
	global_load_dwordx4 v[34:37], v[34:35], off
	s_nop 0
	global_load_dwordx4 v[38:41], v[38:39], off
	v_addc_co_u32_e32 v43, vcc, 0, v137, vcc
	global_load_dwordx4 v[42:45], v[42:43], off
	s_branch .LBB0_1013

.LBB0_1013:
	s_mov_b64 s[38:39], -1
	s_and_b64 vcc, exec, s[12:13]
	s_cbranch_vccz .LBB0_1017
	s_waitcnt vmcnt(14)
	v_mov_b64_e32 v[110:111], v[210:211]
	v_mov_b64_e32 v[112:113], v[212:213]
	v_mov_b64_e32 v[106:107], v[214:215]
	v_mov_b64_e32 v[108:109], v[216:217]
	v_readlane_b32 s6, v248, 44
	v_readlane_b32 s7, v248, 45
	s_nop 1
	v_lshl_add_u64 v[210:211], v[128:129], 0, s[6:7]
	s_mov_b64 s[6:7], 0x9951000
	v_lshl_add_u64 v[214:215], v[210:211], 0, s[6:7]
	global_load_dwordx4 v[210:213], v[214:215], off
	s_nop 0
	global_load_dwordx4 v[214:217], v[214:215], off offset:16
	s_cmp_eq_u32 s0, 0
	s_cbranch_scc1 .Lc_c0loads
	ds_read_b128 v[118:121], v123
	ds_read_b128 v[114:117], v123 offset:16
	ds_read_b128 v[102:105], v123 offset:32
	ds_read_b128 v[98:101], v123 offset:48
	v_lshlrev_b32_e32 v66, 16, v110
	v_and_b32_e32 v67, 0xffff0000, v110
	v_lshlrev_b32_e32 v68, 16, v111
	v_and_b32_e32 v69, 0xffff0000, v111
	v_lshlrev_b32_e32 v70, 16, v112
	v_and_b32_e32 v71, 0xffff0000, v112
	v_lshlrev_b32_e32 v72, 16, v113
	v_and_b32_e32 v73, 0xffff0000, v113
	v_lshlrev_b32_e32 v74, 16, v106
	v_and_b32_e32 v75, 0xffff0000, v106
	v_lshlrev_b32_e32 v76, 16, v107
	v_and_b32_e32 v77, 0xffff0000, v107
	v_lshlrev_b32_e32 v78, 16, v108
	v_and_b32_e32 v79, 0xffff0000, v108
	v_lshlrev_b32_e32 v80, 16, v109
	v_and_b32_e32 v81, 0xffff0000, v109
	v_mul_f32_e32 v82, 0xbfb8aa3b, v66
	v_mul_f32_e32 v83, 0xbfb8aa3b, v67
	v_mul_f32_e32 v84, 0xbfb8aa3b, v68
	v_mul_f32_e32 v85, 0xbfb8aa3b, v69
	v_mul_f32_e32 v86, 0xbfb8aa3b, v70
	v_mul_f32_e32 v87, 0xbfb8aa3b, v71
	v_mul_f32_e32 v88, 0xbfb8aa3b, v72
	v_mul_f32_e32 v89, 0xbfb8aa3b, v73
	v_mul_f32_e32 v2, 0xbfb8aa3b, v74
	v_mul_f32_e32 v3, 0xbfb8aa3b, v75
	v_mul_f32_e32 v4, 0xbfb8aa3b, v76
	v_mul_f32_e32 v5, 0xbfb8aa3b, v77
	v_mul_f32_e32 v22, 0xbfb8aa3b, v78
	v_mul_f32_e32 v23, 0xbfb8aa3b, v79
	v_mul_f32_e32 v24, 0xbfb8aa3b, v80
	v_mul_f32_e32 v25, 0xbfb8aa3b, v81
	s_cmp_gt_u32 s0, 29
	s_cbranch_scc1 .Lc_dl0A
	s_mov_b64 s[6:7], 0x1ad10000
	v_lshl_add_u64 v[26:27], v[136:137], 0, s[6:7]
	global_load_dwordx4 v[26:29], v[26:27], off
.Lc_dl0A:
	v_exp_f32_e32 v82, v82
	v_exp_f32_e32 v83, v83
	v_exp_f32_e32 v84, v84
	v_exp_f32_e32 v85, v85
	v_exp_f32_e32 v86, v86
	v_exp_f32_e32 v87, v87
	v_exp_f32_e32 v88, v88
	v_exp_f32_e32 v89, v89
	v_exp_f32_e32 v2, v2
	v_exp_f32_e32 v3, v3
	v_exp_f32_e32 v4, v4
	v_exp_f32_e32 v5, v5
	v_exp_f32_e32 v22, v22
	v_exp_f32_e32 v23, v23
	v_exp_f32_e32 v24, v24
	v_exp_f32_e32 v25, v25
	s_cmp_gt_u32 s0, 29
	s_cbranch_scc1 .Lc_dl1A
	s_mov_b64 s[6:7], 0x1bd10000
	v_lshl_add_u64 v[30:31], v[136:137], 0, s[6:7]
	global_load_dwordx4 v[30:33], v[30:31], off
.Lc_dl1A:
	v_add_f32_e32 v82, 1.0, v82
	v_add_f32_e32 v83, 1.0, v83
	v_add_f32_e32 v84, 1.0, v84
	v_add_f32_e32 v85, 1.0, v85
	v_add_f32_e32 v86, 1.0, v86
	v_add_f32_e32 v87, 1.0, v87
	v_add_f32_e32 v88, 1.0, v88
	v_add_f32_e32 v89, 1.0, v89
	v_add_f32_e32 v2, 1.0, v2
	v_add_f32_e32 v3, 1.0, v3
	v_add_f32_e32 v4, 1.0, v4
	v_add_f32_e32 v5, 1.0, v5
	v_add_f32_e32 v22, 1.0, v22
	v_add_f32_e32 v23, 1.0, v23
	v_add_f32_e32 v24, 1.0, v24
	v_add_f32_e32 v25, 1.0, v25
	s_waitcnt lgkmcnt(3)
	v_mul_f32_e32 v138, v119, v119
	v_mul_f32_e32 v139, v121, v121
	v_fmac_f32_e32 v138, v118, v118
	v_fmac_f32_e32 v139, v120, v120
	v_add_f32_e32 v144, v138, v139
	s_waitcnt lgkmcnt(2)
	v_pk_mul_f32 v[138:139], v[116:117], v[116:117]
	v_pk_mul_f32 v[140:141], v[114:115], v[114:115]
	v_mov_b32_e32 v142, v138
	v_mov_b32_e32 v143, v140
	v_mov_b32_e32 v140, v139
	v_pk_add_f32 v[138:139], v[142:143], v[140:141]
	s_waitcnt lgkmcnt(1)
	v_pk_mul_f32 v[140:141], v[102:103], v[102:103]
	v_add_f32_e32 v139, v144, v139
	v_add_f32_e32 v144, v138, v139
	v_pk_mul_f32 v[138:139], v[104:105], v[104:105]
	v_mov_b32_e32 v143, v140
	v_mov_b32_e32 v142, v138
	v_mov_b32_e32 v140, v139
	v_pk_add_f32 v[138:139], v[142:143], v[140:141]
	s_waitcnt lgkmcnt(0)
	v_pk_mul_f32 v[140:141], v[98:99], v[98:99]
	v_add_f32_e32 v139, v144, v139
	v_add_f32_e32 v144, v138, v139
	v_pk_mul_f32 v[138:139], v[100:101], v[100:101]
	v_mov_b32_e32 v143, v140
	v_mov_b32_e32 v142, v138
	v_mov_b32_e32 v140, v139
	v_pk_add_f32 v[138:139], v[142:143], v[140:141]
	v_add_f32_e32 v139, v139, v144
	v_add_f32_e32 v138, v138, v139
	s_cmp_gt_u32 s0, 29
	s_cbranch_scc1 .Lc_dl2A
	s_mov_b64 s[6:7], 0x1cd10000
	v_lshl_add_u64 v[34:35], v[136:137], 0, s[6:7]
	global_load_dwordx4 v[34:37], v[34:35], off
.Lc_dl2A:
	s_nop 1
	v_add_f32_dpp v138, v138, v138 quad_perm:[1,0,3,2] row_mask:0xf bank_mask:0xf
	s_nop 1
	v_add_f32_dpp v138, v138, v138 quad_perm:[2,3,0,1] row_mask:0xf bank_mask:0xf
	v_rcp_f32_e32 v82, v82
	v_rcp_f32_e32 v83, v83
	v_rcp_f32_e32 v84, v84
	v_rcp_f32_e32 v85, v85
	v_rcp_f32_e32 v86, v86
	v_rcp_f32_e32 v87, v87
	v_rcp_f32_e32 v88, v88
	v_rcp_f32_e32 v89, v89
	v_rcp_f32_e32 v2, v2
	v_rcp_f32_e32 v3, v3
	v_rcp_f32_e32 v4, v4
	v_rcp_f32_e32 v5, v5
	v_rcp_f32_e32 v22, v22
	v_rcp_f32_e32 v23, v23
	v_rcp_f32_e32 v24, v24
	v_rcp_f32_e32 v25, v25
	s_cmp_gt_u32 s0, 29
	s_cbranch_scc1 .Lc_dl3A
	s_mov_b64 s[6:7], 0x1dd10000
	v_lshl_add_u64 v[38:39], v[136:137], 0, s[6:7]
	global_load_dwordx4 v[38:41], v[38:39], off
.Lc_dl3A:
	v_fmamk_f32 v138, v138, 0x3c800000, v159
	v_cmp_gt_f32_e32 vcc, s26, v138
	v_mul_f32_e32 v139, 0x4f800000, v138
	s_nop 0
	v_cndmask_b32_e32 v138, v138, v139, vcc
	v_sqrt_f32_e32 v139, v138
	s_nop 0
	v_add_u32_e32 v140, -1, v139
	v_fma_f32 v141, -v140, v139, v138
	v_cmp_ge_f32_e64 s[42:43], 0, v141
	v_add_u32_e32 v141, 1, v139
	s_nop 0
	v_cndmask_b32_e64 v140, v139, v140, s[42:43]
	v_fma_f32 v139, -v141, v139, v138
	v_cmp_lt_f32_e64 s[42:43], 0, v139
	s_nop 1
	v_cndmask_b32_e64 v139, v140, v141, s[42:43]
	v_mul_f32_e32 v140, 0x37800000, v139
	v_cndmask_b32_e32 v139, v139, v140, vcc
	v_cmp_class_f32_e32 vcc, v138, v230
	s_nop 1
	v_cndmask_b32_e32 v138, v139, v138, vcc
	v_div_scale_f32 v139, s[6:7], v138, v138, 1.0
	v_rcp_f32_e32 v140, v139
	s_nop 0
	v_fma_f32 v141, -v139, v140, 1.0
	v_fmac_f32_e32 v140, v141, v140
	v_div_scale_f32 v141, vcc, 1.0, v138, 1.0
	v_mul_f32_e32 v142, v141, v140
	v_fma_f32 v143, -v139, v142, v141
	v_fmac_f32_e32 v142, v143, v140
	v_fma_f32 v139, -v139, v142, v141
	v_div_fmas_f32 v139, v139, v140, v142
	v_div_fixup_f32 v140, v139, v138, 1.0
	s_cmp_gt_u32 s0, 29
	s_cbranch_scc1 .Lc_dl4A
	s_mov_b64 s[6:7], 0x13910000
	v_lshl_add_u64 v[42:43], v[136:137], 0, s[6:7]
	global_load_dwordx4 v[42:45], v[42:43], off

.LBB0_1017:
	s_andn2_b64 vcc, exec, s[38:39]
	v_add_u32_e32 v192, 0x800, v152
	v_add_u32_e32 v191, 0x1000, v152
	v_add_u32_e32 v190, 0x1800, v152
	v_add_u32_e32 v189, 0x2000, v152
	v_add_u32_e32 v188, 0x2800, v152
	v_add_u32_e32 v187, 0x3000, v152
	v_add_u32_e32 v186, 0x3800, v152
	v_add_u32_e32 v185, 0x4800, v152
	v_add_u32_e32 v184, 0x5000, v152
	v_add_u32_e32 v183, 0x5800, v152
	v_add_u32_e32 v182, 0x6000, v152
	v_add_u32_e32 v181, 0x6800, v152
	v_add_u32_e32 v180, 0x7000, v152
	v_add_u32_e32 v147, 0x7800, v152
	v_add_u32_e32 v146, 0x8000, v152
	s_cbranch_vccnz .LBB0_1019
	s_and_b64 vcc, exec, s[18:19]
	ds_read_b64 v[106:107], v152
	ds_read_b64 v[108:109], v152 offset:32
	ds_read_b64 v[110:111], v152 offset:64
	ds_read_b64 v[112:113], v152 offset:96
	ds_read_b64 v[114:115], v192 offset:256
	ds_read_b64 v[116:117], v192 offset:288
	ds_read_b64 v[118:119], v192 offset:320
	ds_read_b64 v[120:121], v192 offset:352
	ds_read_b64 v[138:139], v191 offset:512
	ds_read_b64 v[140:141], v191 offset:544
	ds_read_b64 v[142:143], v191 offset:576
	ds_read_b64 v[144:145], v191 offset:608
	ds_read_b64 v[82:83], v190 offset:768
	ds_read_b64 v[84:85], v190 offset:800
	s_cbranch_vccnz .Lc_ml0A
	s_mov_b64 s[6:7], 0x1ad10000
	v_lshl_add_u64 v[26:27], v[136:137], 0, s[6:7]
	global_load_dwordx4 v[26:29], v[26:27], off
.Lc_ml0A:
	v_cvt_pk_bf16_f32 v98, v66, v67
	v_cvt_pk_bf16_f32 v99, v68, v69
	v_cvt_pk_bf16_f32 v100, v70, v71
	v_cvt_pk_bf16_f32 v101, v72, v73
	v_cvt_pk_bf16_f32 v102, v74, v75
	v_cvt_pk_bf16_f32 v103, v76, v77
	v_cvt_pk_bf16_f32 v104, v78, v79
	v_cvt_pk_bf16_f32 v105, v80, v81
	v_pk_mul_f32 v[66:67], v[134:135], v[66:67] op_sel_hi:[0,1]
	v_pk_mul_f32 v[68:69], v[134:135], v[68:69] op_sel_hi:[0,1]
	v_pk_mul_f32 v[70:71], v[134:135], v[70:71] op_sel_hi:[0,1]
	v_pk_mul_f32 v[72:73], v[134:135], v[72:73] op_sel_hi:[0,1]
	v_pk_mul_f32 v[74:75], v[134:135], v[74:75] op_sel_hi:[0,1]
	v_pk_mul_f32 v[76:77], v[134:135], v[76:77] op_sel_hi:[0,1]
	v_pk_mul_f32 v[78:79], v[134:135], v[78:79] op_sel_hi:[0,1]
	v_pk_mul_f32 v[80:81], v[134:135], v[80:81] op_sel_hi:[0,1]
	s_waitcnt lgkmcnt(12)
	v_mfma_f32_16x16x32_bf16 v[106:109], v[106:109], v[98:101], 0
	ds_read_b64 v[86:87], v190 offset:832
	ds_read_b64 v[88:89], v190 offset:864
	ds_read_u16 v193, v178 offset:36864
	s_waitcnt lgkmcnt(13)
	v_mfma_f32_16x16x32_bf16 v[106:109], v[110:113], v[102:105], v[106:109]
	ds_read_u16 v194, v179 offset:36864
	ds_read_u16 v195, v179 offset:37008
	s_waitcnt lgkmcnt(13)
	v_mfma_f32_16x16x32_bf16 v[114:117], v[114:117], v[98:101], 0
	ds_read_u16 v196, v179 offset:37152
	ds_read_u16 v197, v179 offset:39024
	s_waitcnt lgkmcnt(13)
	v_mfma_f32_16x16x32_bf16 v[114:117], v[118:121], v[102:105], v[114:117]
	ds_read_u16 v198, v179 offset:39168
	ds_read_u16 v199, v179 offset:39312
	s_cbranch_vccnz .Lc_ml1A
	s_mov_b64 s[6:7], 0x1bd10000
	v_lshl_add_u64 v[30:31], v[136:137], 0, s[6:7]
	global_load_dwordx4 v[30:33], v[30:31], off
.Lc_ml1A:
	s_waitcnt lgkmcnt(13)
	v_mfma_f32_16x16x32_bf16 v[138:141], v[138:141], v[98:101], 0
	ds_read_u16 v200, v179 offset:39456
	s_waitcnt lgkmcnt(12)
	v_mfma_f32_16x16x32_bf16 v[138:141], v[142:145], v[102:105], v[138:141]
	ds_read_b64 v[210:211], v189 offset:1024
	ds_read_b64 v[212:213], v189 offset:1056
	s_waitcnt lgkmcnt(12)
	v_mfma_f32_16x16x32_bf16 v[82:85], v[82:85], v[98:101], 0
	ds_read_b64 v[214:215], v189 offset:1088
	ds_read_b64 v[216:217], v189 offset:1120
	s_waitcnt lgkmcnt(12)
	v_mfma_f32_16x16x32_bf16 v[82:85], v[86:89], v[102:105], v[82:85]
	ds_read_b64 v[218:219], v188 offset:1280
	ds_read_b64 v[220:221], v188 offset:1312
	s_cbranch_vccnz .Lc_ml2A
	s_mov_b64 s[6:7], 0x1cd10000
	v_lshl_add_u64 v[34:35], v[136:137], 0, s[6:7]
	global_load_dwordx4 v[34:37], v[34:35], off
.Lc_ml2A:
	s_waitcnt lgkmcnt(4)
	v_mfma_f32_16x16x32_bf16 v[210:213], v[210:213], v[98:101], 0
	ds_read_b64 v[222:223], v188 offset:1344
	ds_read_b64 v[224:225], v188 offset:1376
	ds_read_b64 v[2:3], v187 offset:1536
	ds_read_b64 v[4:5], v187 offset:1568
	ds_read_b64 v[22:23], v187 offset:1600
	ds_read_b64 v[24:25], v187 offset:1632
	ds_read_b64 v[6:7], v186 offset:1792
	ds_read_b64 v[8:9], v186 offset:1824
	ds_read_b64 v[10:11], v186 offset:1856
	ds_read_b64 v[12:13], v186 offset:1888
	s_waitcnt lgkmcnt(12)
	v_mfma_f32_16x16x32_bf16 v[210:213], v[214:217], v[102:105], v[210:213]
	ds_read_b64 v[14:15], v185
	ds_read_b64 v[16:17], v185 offset:32
	s_waitcnt lgkmcnt(12)
	v_mfma_f32_16x16x32_bf16 v[218:221], v[218:221], v[98:101], 0
	ds_read_b64 v[18:19], v184 offset:256
	ds_read_b64 v[20:21], v184 offset:288
	s_waitcnt lgkmcnt(12)
	v_mfma_f32_16x16x32_bf16 v[218:221], v[222:225], v[102:105], v[218:221]
	ds_read_b64 v[90:91], v183 offset:512
	ds_read_b64 v[92:93], v183 offset:544
	s_cbranch_vccnz .Lc_ml3A
	s_mov_b64 s[6:7], 0x1dd10000
	v_lshl_add_u64 v[38:39], v[136:137], 0, s[6:7]
	global_load_dwordx4 v[38:41], v[38:39], off
.Lc_ml3A:
	s_waitcnt lgkmcnt(12)
	v_mfma_f32_16x16x32_bf16 v[2:5], v[2:5], v[98:101], 0
	ds_read_b64 v[238:239], v182 offset:768
	ds_read_b64 v[240:241], v182 offset:800
	ds_read_u16 v201, v179 offset:41328
	s_waitcnt lgkmcnt(13)
	v_mfma_f32_16x16x32_bf16 v[2:5], v[22:25], v[102:105], v[2:5]
	ds_read_u16 v202, v179 offset:41472
	ds_read_u16 v203, v179 offset:41616
	s_waitcnt lgkmcnt(13)
	v_mfma_f32_16x16x32_bf16 v[6:9], v[6:9], v[98:101], 0
	ds_read_u16 v204, v179 offset:41760
	ds_read_u16 v205, v179 offset:43632
	s_waitcnt lgkmcnt(13)
	v_mfma_f32_16x16x32_bf16 v[6:9], v[10:13], v[102:105], v[6:9]
	ds_read_u16 v206, v179 offset:43776
	ds_read_u16 v207, v179 offset:43920
	s_cbranch_vccnz .Lc_ml4A
	s_mov_b64 s[6:7], 0x13910000
	v_lshl_add_u64 v[42:43], v[136:137], 0, s[6:7]
	global_load_dwordx4 v[42:45], v[42:43], off
.Lc_ml4A:
	v_lshlrev_b32_e32 v193, 16, v193
	v_lshlrev_b32_e32 v194, 16, v194
	v_lshlrev_b32_e32 v195, 16, v195
	v_lshlrev_b32_e32 v196, 16, v196
	v_lshlrev_b32_e32 v197, 16, v197
	v_lshlrev_b32_e32 v198, 16, v198
	v_lshlrev_b32_e32 v199, 16, v199
	v_lshlrev_b32_e32 v200, 16, v200
	v_sub_f32_e32 v106, v193, v106
	v_sub_f32_e32 v107, v194, v107
	v_sub_f32_e32 v108, v195, v108
	v_sub_f32_e32 v109, v196, v109
	v_sub_f32_e32 v114, v197, v114
	v_sub_f32_e32 v115, v198, v115
	v_sub_f32_e32 v116, v199, v116
	v_sub_f32_e32 v117, v200, v117
	v_cvt_pk_bf16_f32 v194, v106, v107
	v_cvt_pk_bf16_f32 v195, v108, v109
	v_cvt_pk_bf16_f32 v196, v114, v115
	v_cvt_pk_bf16_f32 v197, v116, v117
	s_nop 1
	s_waitcnt lgkmcnt(13)
	v_mfma_f32_16x16x32_bf16 v[210:213], v[14:17], v[194:197], v[210:213]
	ds_read_u16 v208, v179 offset:44064
	s_waitcnt lgkmcnt(12)
	v_mfma_f32_16x16x32_bf16 v[218:221], v[18:21], v[194:197], v[218:221]
	ds_read_b64 v[94:95], v183 offset:576
	ds_read_b64 v[96:97], v183 offset:608
	s_waitcnt lgkmcnt(12)
	v_mfma_f32_16x16x32_bf16 v[2:5], v[90:93], v[194:197], v[2:5]
	ds_read_b64 v[242:243], v182 offset:832
	ds_read_b64 v[244:245], v182 offset:864
	s_waitcnt lgkmcnt(12)
	v_mfma_f32_16x16x32_bf16 v[6:9], v[238:241], v[194:197], v[6:9]
	ds_read_b64 v[110:111], v181 offset:1024
	ds_read_b64 v[112:113], v181 offset:1056
	s_waitcnt lgkmcnt(6)
	v_lshlrev_b32_e32 v201, 16, v201
	v_lshlrev_b32_e32 v202, 16, v202
	v_lshlrev_b32_e32 v203, 16, v203
	v_lshlrev_b32_e32 v204, 16, v204
	v_lshlrev_b32_e32 v205, 16, v205
	v_lshlrev_b32_e32 v206, 16, v206
	v_lshlrev_b32_e32 v207, 16, v207
	v_lshlrev_b32_e32 v208, 16, v208
	v_sub_f32_e32 v138, v201, v138
	v_sub_f32_e32 v139, v202, v139
	v_sub_f32_e32 v140, v203, v140
	v_sub_f32_e32 v141, v204, v141
	v_sub_f32_e32 v82, v205, v82
	v_sub_f32_e32 v83, v206, v83
	v_sub_f32_e32 v84, v207, v84
	v_sub_f32_e32 v85, v208, v85
	v_cvt_pk_bf16_f32 v202, v138, v139
	v_cvt_pk_bf16_f32 v203, v140, v141
	v_cvt_pk_bf16_f32 v204, v82, v83
	v_cvt_pk_bf16_f32 v205, v84, v85
	s_nop 1
	ds_read_b64 v[118:119], v180 offset:1280
	ds_read_b64 v[120:121], v180 offset:1312
	ds_read_b64 v[142:143], v147 offset:1536
	ds_read_b64 v[144:145], v147 offset:1568
	ds_read_b64 v[86:87], v146 offset:1792
	ds_read_b64 v[88:89], v146 offset:1824
	ds_read_b64 v[214:215], v181 offset:1088
	ds_read_b64 v[216:217], v181 offset:1120
	s_waitcnt lgkmcnt(12)
	v_mfma_f32_16x16x32_bf16 v[2:5], v[94:97], v[202:205], v[2:5]
	ds_read_b64 v[222:223], v180 offset:1344
	ds_read_b64 v[224:225], v180 offset:1376
	s_waitcnt lgkmcnt(12)
	v_mfma_f32_16x16x32_bf16 v[6:9], v[242:245], v[202:205], v[6:9]
	ds_read_b64 v[22:23], v147 offset:1600
	ds_read_b64 v[24:25], v147 offset:1632
	s_waitcnt lgkmcnt(12)
	v_mfma_f32_16x16x32_bf16 v[66:69], v[110:113], v[194:197], v[66:69]
	ds_read_b64 v[10:11], v146 offset:1856
	ds_read_b64 v[12:13], v146 offset:1888
	s_waitcnt lgkmcnt(12)
	v_mfma_f32_16x16x32_bf16 v[70:73], v[118:121], v[194:197], v[70:73]
	s_waitcnt lgkmcnt(10)
	v_mfma_f32_16x16x32_bf16 v[74:77], v[142:145], v[194:197], v[74:77]
	s_waitcnt lgkmcnt(8)
	v_mfma_f32_16x16x32_bf16 v[78:81], v[86:89], v[194:197], v[78:81]
	s_waitcnt lgkmcnt(6)
	v_mfma_f32_16x16x32_bf16 v[66:69], v[214:217], v[202:205], v[66:69]
	s_waitcnt lgkmcnt(4)
	v_mfma_f32_16x16x32_bf16 v[70:73], v[222:225], v[202:205], v[70:73]
	s_waitcnt lgkmcnt(2)
	v_mfma_f32_16x16x32_bf16 v[74:77], v[22:25], v[202:205], v[74:77]
	s_waitcnt lgkmcnt(0)
	v_mfma_f32_16x16x32_bf16 v[78:81], v[10:13], v[202:205], v[78:81]
	v_add_u32_e32 v226, v150, v153
	ds_write_b32 v226, v210 offset:53248
	v_add_u32_e32 v227, v150, v154
	ds_write_b32 v227, v211 offset:53248
	v_add_u32_e32 v226, v150, v155
	ds_write_b32 v226, v212 offset:53248
	v_add_u32_e32 v227, v150, v156
	ds_write_b32 v227, v213 offset:53248
	v_add_u32_e32 v226, v150, v157
	ds_write_b32 v226, v218 offset:53248
	v_add_u32_e32 v227, v150, v167
	ds_write_b32 v227, v219 offset:53248
	v_add_u32_e32 v226, v150, v168
	ds_write_b32 v226, v220 offset:53248
	v_add_u32_e32 v227, v150, v169
	ds_write_b32 v227, v221 offset:53248
	v_add_u32_e32 v226, v150, v170
	ds_write_b32 v226, v2 offset:53248
	v_add_u32_e32 v227, v150, v171
	ds_write_b32 v227, v3 offset:53248
	v_add_u32_e32 v226, v150, v172
	ds_write_b32 v226, v4 offset:53248
	v_add_u32_e32 v227, v150, v173
	ds_write_b32 v227, v5 offset:53248
	v_add_u32_e32 v226, v150, v174
	ds_write_b32 v226, v6 offset:53248
	v_add_u32_e32 v227, v150, v175
	ds_write_b32 v227, v7 offset:53248
	v_add_u32_e32 v226, v150, v176
	ds_write_b32 v226, v8 offset:53248
	v_add_u32_e32 v227, v150, v177
	ds_write_b32 v227, v9 offset:53248

.Lc_mid_go:
	s_cmp_gt_u32 s0, 28
	v_readlane_b32 s9, v249, 50
	ds_write_b128 v148, v[46:49]
	ds_write_b128 v148, v[50:53] offset:9216
	ds_write_b128 v148, v[54:57] offset:18432
	ds_write_b128 v148, v[58:61] offset:27648
	ds_write_b128 v148, v[62:65] offset:36864
	s_waitcnt lgkmcnt(0)
	s_barrier
	s_cbranch_scc1 .LBB0_1022
	s_branch .LBB0_1022
	v_add_co_u32_e32 v46, vcc, 0x1ad18000, v136
	s_nop 0
	s_nop 0
	v_addc_co_u32_e32 v47, vcc, 0, v137, vcc
	v_add_co_u32_e32 v50, vcc, 0x1bd18000, v136
	s_nop 0
	s_nop 0
	v_addc_co_u32_e32 v51, vcc, 0, v137, vcc
	v_add_co_u32_e32 v54, vcc, 0x1cd18000, v136
	global_load_dwordx4 v[46:49], v[46:47], off
	s_nop 0
	global_load_dwordx4 v[50:53], v[50:51], off
	v_addc_co_u32_e32 v55, vcc, 0, v137, vcc
	v_add_co_u32_e32 v58, vcc, 0x1dd18000, v136
	s_nop 0
	s_nop 0
	v_addc_co_u32_e32 v59, vcc, 0, v137, vcc
	v_add_co_u32_e32 v62, vcc, 0x13918000, v136
	global_load_dwordx4 v[54:57], v[54:55], off
	s_nop 0
	global_load_dwordx4 v[58:61], v[58:59], off
	v_addc_co_u32_e32 v63, vcc, 0, v137, vcc
	global_load_dwordx4 v[62:65], v[62:63], off

.Lc_noze:
	ds_read_b128 v[118:121], v166 offset:53248
	ds_read_b128 v[114:117], v166 offset:53264
	ds_read_b128 v[110:113], v166 offset:53280
	ds_read_b128 v[106:109], v166 offset:53296
	v_lshlrev_b32_e32 v66, 16, v94
	v_and_b32_e32 v67, 0xffff0000, v94
	v_lshlrev_b32_e32 v68, 16, v95
	v_and_b32_e32 v69, 0xffff0000, v95
	v_lshlrev_b32_e32 v70, 16, v96
	v_and_b32_e32 v71, 0xffff0000, v96
	v_lshlrev_b32_e32 v72, 16, v97
	v_and_b32_e32 v73, 0xffff0000, v97
	v_lshlrev_b32_e32 v74, 16, v90
	v_and_b32_e32 v75, 0xffff0000, v90
	v_lshlrev_b32_e32 v76, 16, v91
	v_and_b32_e32 v77, 0xffff0000, v91
	v_lshlrev_b32_e32 v78, 16, v92
	v_and_b32_e32 v79, 0xffff0000, v92
	v_lshlrev_b32_e32 v80, 16, v93
	v_and_b32_e32 v81, 0xffff0000, v93
	v_mul_f32_e32 v82, 0xbfb8aa3b, v66
	v_mul_f32_e32 v83, 0xbfb8aa3b, v67
	v_mul_f32_e32 v84, 0xbfb8aa3b, v68
	v_mul_f32_e32 v85, 0xbfb8aa3b, v69
	v_mul_f32_e32 v86, 0xbfb8aa3b, v70
	v_mul_f32_e32 v87, 0xbfb8aa3b, v71
	v_mul_f32_e32 v88, 0xbfb8aa3b, v72
	v_mul_f32_e32 v89, 0xbfb8aa3b, v73
	v_mul_f32_e32 v2, 0xbfb8aa3b, v74
	v_mul_f32_e32 v3, 0xbfb8aa3b, v75
	v_mul_f32_e32 v4, 0xbfb8aa3b, v76
	v_mul_f32_e32 v5, 0xbfb8aa3b, v77
	v_mul_f32_e32 v22, 0xbfb8aa3b, v78
	v_mul_f32_e32 v23, 0xbfb8aa3b, v79
	v_mul_f32_e32 v24, 0xbfb8aa3b, v80
	v_mul_f32_e32 v25, 0xbfb8aa3b, v81
	s_cmp_gt_u32 s0, 28
	s_cbranch_scc1 .Lc_dl0B
	s_mov_b64 s[6:7], 0x1ad18000
	v_lshl_add_u64 v[46:47], v[136:137], 0, s[6:7]
	global_load_dwordx4 v[46:49], v[46:47], off
.Lc_dl0B:
	v_exp_f32_e32 v82, v82
	v_exp_f32_e32 v83, v83
	v_exp_f32_e32 v84, v84
	v_exp_f32_e32 v85, v85
	v_exp_f32_e32 v86, v86
	v_exp_f32_e32 v87, v87
	v_exp_f32_e32 v88, v88
	v_exp_f32_e32 v89, v89
	v_exp_f32_e32 v2, v2
	v_exp_f32_e32 v3, v3
	v_exp_f32_e32 v4, v4
	v_exp_f32_e32 v5, v5
	v_exp_f32_e32 v22, v22
	v_exp_f32_e32 v23, v23
	v_exp_f32_e32 v24, v24
	v_exp_f32_e32 v25, v25
	s_cmp_gt_u32 s0, 28
	s_cbranch_scc1 .Lc_dl1B
	s_mov_b64 s[6:7], 0x1bd18000
	v_lshl_add_u64 v[50:51], v[136:137], 0, s[6:7]
	global_load_dwordx4 v[50:53], v[50:51], off
.Lc_dl1B:
	v_add_f32_e32 v82, 1.0, v82
	v_add_f32_e32 v83, 1.0, v83
	v_add_f32_e32 v84, 1.0, v84
	v_add_f32_e32 v85, 1.0, v85
	v_add_f32_e32 v86, 1.0, v86
	v_add_f32_e32 v87, 1.0, v87
	v_add_f32_e32 v88, 1.0, v88
	v_add_f32_e32 v89, 1.0, v89
	v_add_f32_e32 v2, 1.0, v2
	v_add_f32_e32 v3, 1.0, v3
	v_add_f32_e32 v4, 1.0, v4
	v_add_f32_e32 v5, 1.0, v5
	v_add_f32_e32 v22, 1.0, v22
	v_add_f32_e32 v23, 1.0, v23
	v_add_f32_e32 v24, 1.0, v24
	v_add_f32_e32 v25, 1.0, v25
	s_waitcnt lgkmcnt(3)
	v_mul_f32_e32 v138, v119, v119
	v_mul_f32_e32 v139, v121, v121
	v_fmac_f32_e32 v138, v118, v118
	v_fmac_f32_e32 v139, v120, v120
	v_add_f32_e32 v144, v138, v139
	s_waitcnt lgkmcnt(2)
	v_pk_mul_f32 v[138:139], v[116:117], v[116:117]
	v_pk_mul_f32 v[140:141], v[114:115], v[114:115]
	v_mov_b32_e32 v142, v138
	v_mov_b32_e32 v143, v140
	v_mov_b32_e32 v140, v139
	v_pk_add_f32 v[138:139], v[142:143], v[140:141]
	s_waitcnt lgkmcnt(1)
	v_pk_mul_f32 v[140:141], v[110:111], v[110:111]
	v_add_f32_e32 v139, v144, v139
	v_add_f32_e32 v144, v138, v139
	v_pk_mul_f32 v[138:139], v[112:113], v[112:113]
	v_mov_b32_e32 v143, v140
	v_mov_b32_e32 v142, v138
	v_mov_b32_e32 v140, v139
	v_pk_add_f32 v[138:139], v[142:143], v[140:141]
	s_waitcnt lgkmcnt(0)
	v_pk_mul_f32 v[140:141], v[106:107], v[106:107]
	v_add_f32_e32 v139, v144, v139
	v_add_f32_e32 v144, v138, v139
	v_pk_mul_f32 v[138:139], v[108:109], v[108:109]
	v_mov_b32_e32 v143, v140
	v_mov_b32_e32 v142, v138
	v_mov_b32_e32 v140, v139
	v_pk_add_f32 v[138:139], v[142:143], v[140:141]
	v_add_f32_e32 v139, v139, v144
	v_add_f32_e32 v138, v138, v139
	s_cmp_gt_u32 s0, 28
	s_cbranch_scc1 .Lc_dl2B
	s_mov_b64 s[6:7], 0x1cd18000
	v_lshl_add_u64 v[54:55], v[136:137], 0, s[6:7]
	global_load_dwordx4 v[54:57], v[54:55], off
.Lc_dl2B:
	s_nop 1
	v_add_f32_dpp v138, v138, v138 quad_perm:[1,0,3,2] row_mask:0xf bank_mask:0xf
	s_nop 1
	v_add_f32_dpp v138, v138, v138 quad_perm:[2,3,0,1] row_mask:0xf bank_mask:0xf
	v_rcp_f32_e32 v82, v82
	v_rcp_f32_e32 v83, v83
	v_rcp_f32_e32 v84, v84
	v_rcp_f32_e32 v85, v85
	v_rcp_f32_e32 v86, v86
	v_rcp_f32_e32 v87, v87
	v_rcp_f32_e32 v88, v88
	v_rcp_f32_e32 v89, v89
	v_rcp_f32_e32 v2, v2
	v_rcp_f32_e32 v3, v3
	v_rcp_f32_e32 v4, v4
	v_rcp_f32_e32 v5, v5
	v_rcp_f32_e32 v22, v22
	v_rcp_f32_e32 v23, v23
	v_rcp_f32_e32 v24, v24
	v_rcp_f32_e32 v25, v25
	s_cmp_gt_u32 s0, 28
	s_cbranch_scc1 .Lc_dl3B
	s_mov_b64 s[6:7], 0x1dd18000
	v_lshl_add_u64 v[58:59], v[136:137], 0, s[6:7]
	global_load_dwordx4 v[58:61], v[58:59], off
.Lc_dl3B:
	v_fmamk_f32 v138, v138, 0x3c800000, v159
	v_cmp_gt_f32_e32 vcc, s26, v138
	v_mul_f32_e32 v139, 0x4f800000, v138
	s_nop 0
	v_cndmask_b32_e32 v138, v138, v139, vcc
	v_sqrt_f32_e32 v139, v138
	s_nop 0
	v_add_u32_e32 v140, -1, v139
	v_fma_f32 v141, -v140, v139, v138
	v_cmp_ge_f32_e64 s[42:43], 0, v141
	v_add_u32_e32 v141, 1, v139
	s_nop 0
	v_cndmask_b32_e64 v140, v139, v140, s[42:43]
	v_fma_f32 v139, -v141, v139, v138
	v_cmp_lt_f32_e64 s[42:43], 0, v139
	s_nop 1
	v_cndmask_b32_e64 v139, v140, v141, s[42:43]
	v_mul_f32_e32 v140, 0x37800000, v139
	v_cndmask_b32_e32 v139, v139, v140, vcc
	v_cmp_class_f32_e32 vcc, v138, v230
	s_nop 1
	v_cndmask_b32_e32 v138, v139, v138, vcc
	v_div_scale_f32 v139, s[6:7], v138, v138, 1.0
	v_rcp_f32_e32 v140, v139
	s_nop 0
	v_fma_f32 v141, -v139, v140, 1.0
	v_fmac_f32_e32 v140, v141, v140
	v_div_scale_f32 v141, vcc, 1.0, v138, 1.0
	v_mul_f32_e32 v142, v141, v140
	v_fma_f32 v143, -v139, v142, v141
	v_fmac_f32_e32 v142, v143, v140
	v_fma_f32 v139, -v139, v142, v141
	v_div_fmas_f32 v139, v139, v140, v142
	v_div_fixup_f32 v140, v139, v138, 1.0
	s_cmp_gt_u32 s0, 28
	s_cbranch_scc1 .Lc_dl4B
	s_mov_b64 s[6:7], 0x13918000
	v_lshl_add_u64 v[62:63], v[136:137], 0, s[6:7]
	global_load_dwordx4 v[62:65], v[62:63], off

.LBB0_1024:
	s_andn2_b64 vcc, exec, s[20:21]
	s_cbranch_vccnz .LBB0_1026
	s_cmp_gt_u32 s0, 28
	s_cselect_b64 vcc, -1, 0
	ds_read_b64 v[106:107], v152
	ds_read_b64 v[108:109], v152 offset:32
	ds_read_b64 v[110:111], v152 offset:64
	ds_read_b64 v[112:113], v152 offset:96
	ds_read_b64 v[114:115], v192 offset:256
	ds_read_b64 v[116:117], v192 offset:288
	ds_read_b64 v[118:119], v192 offset:320
	ds_read_b64 v[120:121], v192 offset:352
	ds_read_b64 v[138:139], v191 offset:512
	ds_read_b64 v[140:141], v191 offset:544
	ds_read_b64 v[142:143], v191 offset:576
	ds_read_b64 v[144:145], v191 offset:608
	ds_read_b64 v[82:83], v190 offset:768
	ds_read_b64 v[84:85], v190 offset:800
	s_cbranch_vccnz .Lc_ml0B
	s_mov_b64 s[6:7], 0x1ad18000
	v_lshl_add_u64 v[46:47], v[136:137], 0, s[6:7]
	global_load_dwordx4 v[46:49], v[46:47], off
.Lc_ml0B:
	v_cvt_pk_bf16_f32 v90, v66, v67
	v_cvt_pk_bf16_f32 v91, v68, v69
	v_cvt_pk_bf16_f32 v92, v70, v71
	v_cvt_pk_bf16_f32 v93, v72, v73
	v_cvt_pk_bf16_f32 v94, v74, v75
	v_cvt_pk_bf16_f32 v95, v76, v77
	v_cvt_pk_bf16_f32 v96, v78, v79
	v_cvt_pk_bf16_f32 v97, v80, v81
	v_pk_mul_f32 v[66:67], v[0:1], v[66:67] op_sel_hi:[0,1]
	v_pk_mul_f32 v[68:69], v[0:1], v[68:69] op_sel_hi:[0,1]
	v_pk_mul_f32 v[70:71], v[0:1], v[70:71] op_sel_hi:[0,1]
	v_pk_mul_f32 v[72:73], v[0:1], v[72:73] op_sel_hi:[0,1]
	v_pk_mul_f32 v[74:75], v[0:1], v[74:75] op_sel_hi:[0,1]
	v_pk_mul_f32 v[76:77], v[0:1], v[76:77] op_sel_hi:[0,1]
	v_pk_mul_f32 v[78:79], v[0:1], v[78:79] op_sel_hi:[0,1]
	v_pk_mul_f32 v[80:81], v[0:1], v[80:81] op_sel_hi:[0,1]
	s_waitcnt lgkmcnt(12)
	v_mfma_f32_16x16x32_bf16 v[106:109], v[106:109], v[90:93], 0
	ds_read_b64 v[86:87], v190 offset:832
	ds_read_b64 v[88:89], v190 offset:864
	ds_read_u16 v193, v178 offset:36864
	s_waitcnt lgkmcnt(13)
	v_mfma_f32_16x16x32_bf16 v[106:109], v[110:113], v[94:97], v[106:109]
	ds_read_u16 v194, v179 offset:36864
	ds_read_u16 v195, v179 offset:37008
	s_waitcnt lgkmcnt(13)
	v_mfma_f32_16x16x32_bf16 v[114:117], v[114:117], v[90:93], 0
	ds_read_u16 v196, v179 offset:37152
	ds_read_u16 v197, v179 offset:39024
	s_waitcnt lgkmcnt(13)
	v_mfma_f32_16x16x32_bf16 v[114:117], v[118:121], v[94:97], v[114:117]
	ds_read_u16 v198, v179 offset:39168
	ds_read_u16 v199, v179 offset:39312
	s_cbranch_vccnz .Lc_ml1B
	s_mov_b64 s[6:7], 0x1bd18000
	v_lshl_add_u64 v[50:51], v[136:137], 0, s[6:7]
	global_load_dwordx4 v[50:53], v[50:51], off
.Lc_ml1B:
	s_waitcnt lgkmcnt(13)
	v_mfma_f32_16x16x32_bf16 v[138:141], v[138:141], v[90:93], 0
	ds_read_u16 v200, v179 offset:39456
	s_waitcnt lgkmcnt(12)
	v_mfma_f32_16x16x32_bf16 v[138:141], v[142:145], v[94:97], v[138:141]
	ds_read_b64 v[210:211], v189 offset:1024
	ds_read_b64 v[212:213], v189 offset:1056
	s_waitcnt lgkmcnt(12)
	v_mfma_f32_16x16x32_bf16 v[82:85], v[82:85], v[90:93], 0
	ds_read_b64 v[214:215], v189 offset:1088
	ds_read_b64 v[216:217], v189 offset:1120
	s_waitcnt lgkmcnt(12)
	v_mfma_f32_16x16x32_bf16 v[82:85], v[86:89], v[94:97], v[82:85]
	ds_read_b64 v[218:219], v188 offset:1280
	ds_read_b64 v[220:221], v188 offset:1312
	s_cbranch_vccnz .Lc_ml2B
	s_mov_b64 s[6:7], 0x1cd18000
	v_lshl_add_u64 v[54:55], v[136:137], 0, s[6:7]
	global_load_dwordx4 v[54:57], v[54:55], off
.Lc_ml2B:
	s_waitcnt lgkmcnt(4)
	v_mfma_f32_16x16x32_bf16 v[210:213], v[210:213], v[90:93], 0
	ds_read_b64 v[222:223], v188 offset:1344
	ds_read_b64 v[224:225], v188 offset:1376
	ds_read_b64 v[2:3], v187 offset:1536
	ds_read_b64 v[4:5], v187 offset:1568
	ds_read_b64 v[22:23], v187 offset:1600
	ds_read_b64 v[24:25], v187 offset:1632
	ds_read_b64 v[6:7], v186 offset:1792
	ds_read_b64 v[8:9], v186 offset:1824
	ds_read_b64 v[10:11], v186 offset:1856
	ds_read_b64 v[12:13], v186 offset:1888
	s_waitcnt lgkmcnt(12)
	v_mfma_f32_16x16x32_bf16 v[210:213], v[214:217], v[94:97], v[210:213]
	ds_read_b64 v[14:15], v185
	ds_read_b64 v[16:17], v185 offset:32
	s_waitcnt lgkmcnt(12)
	v_mfma_f32_16x16x32_bf16 v[218:221], v[218:221], v[90:93], 0
	ds_read_b64 v[18:19], v184 offset:256
	ds_read_b64 v[20:21], v184 offset:288
	s_waitcnt lgkmcnt(12)
	v_mfma_f32_16x16x32_bf16 v[218:221], v[222:225], v[94:97], v[218:221]
	ds_read_b64 v[98:99], v183 offset:512
	ds_read_b64 v[100:101], v183 offset:544
	s_cbranch_vccnz .Lc_ml3B
	s_mov_b64 s[6:7], 0x1dd18000
	v_lshl_add_u64 v[58:59], v[136:137], 0, s[6:7]
	global_load_dwordx4 v[58:61], v[58:59], off
.Lc_ml3B:
	s_waitcnt lgkmcnt(12)
	v_mfma_f32_16x16x32_bf16 v[2:5], v[2:5], v[90:93], 0
	ds_read_b64 v[238:239], v182 offset:768
	ds_read_b64 v[240:241], v182 offset:800
	ds_read_u16 v201, v179 offset:41328
	s_waitcnt lgkmcnt(13)
	v_mfma_f32_16x16x32_bf16 v[2:5], v[22:25], v[94:97], v[2:5]
	ds_read_u16 v202, v179 offset:41472
	ds_read_u16 v203, v179 offset:41616
	s_waitcnt lgkmcnt(13)
	v_mfma_f32_16x16x32_bf16 v[6:9], v[6:9], v[90:93], 0
	ds_read_u16 v204, v179 offset:41760
	ds_read_u16 v205, v179 offset:43632
	s_waitcnt lgkmcnt(13)
	v_mfma_f32_16x16x32_bf16 v[6:9], v[10:13], v[94:97], v[6:9]
	ds_read_u16 v206, v179 offset:43776
	ds_read_u16 v207, v179 offset:43920
	s_cbranch_vccnz .Lc_ml4B
	s_mov_b64 s[6:7], 0x13918000
	v_lshl_add_u64 v[62:63], v[136:137], 0, s[6:7]
	global_load_dwordx4 v[62:65], v[62:63], off
.Lc_ml4B:
	v_lshlrev_b32_e32 v193, 16, v193
	v_lshlrev_b32_e32 v194, 16, v194
	v_lshlrev_b32_e32 v195, 16, v195
	v_lshlrev_b32_e32 v196, 16, v196
	v_lshlrev_b32_e32 v197, 16, v197
	v_lshlrev_b32_e32 v198, 16, v198
	v_lshlrev_b32_e32 v199, 16, v199
	v_lshlrev_b32_e32 v200, 16, v200
	v_sub_f32_e32 v106, v193, v106
	v_sub_f32_e32 v107, v194, v107
	v_sub_f32_e32 v108, v195, v108
	v_sub_f32_e32 v109, v196, v109
	v_sub_f32_e32 v114, v197, v114
	v_sub_f32_e32 v115, v198, v115
	v_sub_f32_e32 v116, v199, v116
	v_sub_f32_e32 v117, v200, v117
	v_cvt_pk_bf16_f32 v194, v106, v107
	v_cvt_pk_bf16_f32 v195, v108, v109
	v_cvt_pk_bf16_f32 v196, v114, v115
	v_cvt_pk_bf16_f32 v197, v116, v117
	s_nop 1
	s_waitcnt lgkmcnt(13)
	v_mfma_f32_16x16x32_bf16 v[210:213], v[14:17], v[194:197], v[210:213]
	ds_read_u16 v208, v179 offset:44064
	s_waitcnt lgkmcnt(12)
	v_mfma_f32_16x16x32_bf16 v[218:221], v[18:21], v[194:197], v[218:221]
	ds_read_b64 v[102:103], v183 offset:576
	ds_read_b64 v[104:105], v183 offset:608
	s_waitcnt lgkmcnt(12)
	v_mfma_f32_16x16x32_bf16 v[2:5], v[98:101], v[194:197], v[2:5]
	ds_read_b64 v[242:243], v182 offset:832
	ds_read_b64 v[244:245], v182 offset:864
	s_waitcnt lgkmcnt(12)
	v_mfma_f32_16x16x32_bf16 v[6:9], v[238:241], v[194:197], v[6:9]
	ds_read_b64 v[110:111], v181 offset:1024
	ds_read_b64 v[112:113], v181 offset:1056
	s_waitcnt lgkmcnt(6)
	v_lshlrev_b32_e32 v201, 16, v201
	v_lshlrev_b32_e32 v202, 16, v202
	v_lshlrev_b32_e32 v203, 16, v203
	v_lshlrev_b32_e32 v204, 16, v204
	v_lshlrev_b32_e32 v205, 16, v205
	v_lshlrev_b32_e32 v206, 16, v206
	v_lshlrev_b32_e32 v207, 16, v207
	v_lshlrev_b32_e32 v208, 16, v208
	v_sub_f32_e32 v138, v201, v138
	v_sub_f32_e32 v139, v202, v139
	v_sub_f32_e32 v140, v203, v140
	v_sub_f32_e32 v141, v204, v141
	v_sub_f32_e32 v82, v205, v82
	v_sub_f32_e32 v83, v206, v83
	v_sub_f32_e32 v84, v207, v84
	v_sub_f32_e32 v85, v208, v85
	v_cvt_pk_bf16_f32 v202, v138, v139
	v_cvt_pk_bf16_f32 v203, v140, v141
	v_cvt_pk_bf16_f32 v204, v82, v83
	v_cvt_pk_bf16_f32 v205, v84, v85
	s_nop 1
	ds_read_b64 v[118:119], v180 offset:1280
	ds_read_b64 v[120:121], v180 offset:1312
	ds_read_b64 v[142:143], v147 offset:1536
	ds_read_b64 v[144:145], v147 offset:1568
	ds_read_b64 v[86:87], v146 offset:1792
	ds_read_b64 v[88:89], v146 offset:1824
	ds_read_b64 v[214:215], v181 offset:1088
	ds_read_b64 v[216:217], v181 offset:1120
	s_waitcnt lgkmcnt(12)
	v_mfma_f32_16x16x32_bf16 v[2:5], v[102:105], v[202:205], v[2:5]
	ds_read_b64 v[222:223], v180 offset:1344
	ds_read_b64 v[224:225], v180 offset:1376
	s_waitcnt lgkmcnt(12)
	v_mfma_f32_16x16x32_bf16 v[6:9], v[242:245], v[202:205], v[6:9]
	ds_read_b64 v[22:23], v147 offset:1600
	ds_read_b64 v[24:25], v147 offset:1632
	s_waitcnt lgkmcnt(12)
	v_mfma_f32_16x16x32_bf16 v[66:69], v[110:113], v[194:197], v[66:69]
	ds_read_b64 v[10:11], v146 offset:1856
	ds_read_b64 v[12:13], v146 offset:1888
	s_waitcnt lgkmcnt(12)
	v_mfma_f32_16x16x32_bf16 v[70:73], v[118:121], v[194:197], v[70:73]
	s_waitcnt lgkmcnt(10)
	v_mfma_f32_16x16x32_bf16 v[74:77], v[142:145], v[194:197], v[74:77]
	s_waitcnt lgkmcnt(8)
	v_mfma_f32_16x16x32_bf16 v[78:81], v[86:89], v[194:197], v[78:81]
	s_waitcnt lgkmcnt(6)
	v_mfma_f32_16x16x32_bf16 v[66:69], v[214:217], v[202:205], v[66:69]
	s_waitcnt lgkmcnt(4)
	v_mfma_f32_16x16x32_bf16 v[70:73], v[222:225], v[202:205], v[70:73]
	s_waitcnt lgkmcnt(2)
	v_mfma_f32_16x16x32_bf16 v[74:77], v[22:25], v[202:205], v[74:77]
	s_waitcnt lgkmcnt(0)
	v_mfma_f32_16x16x32_bf16 v[78:81], v[10:13], v[202:205], v[78:81]
	v_add_u32_e32 v226, v151, v153
	ds_write_b32 v226, v210
	v_add_u32_e32 v227, v151, v154
	ds_write_b32 v227, v211
	v_add_u32_e32 v226, v151, v155
	ds_write_b32 v226, v212
	v_add_u32_e32 v227, v151, v156
	ds_write_b32 v227, v213
	v_add_u32_e32 v226, v151, v157
	ds_write_b32 v226, v218
	v_add_u32_e32 v227, v151, v167
	ds_write_b32 v227, v219
	v_add_u32_e32 v226, v151, v168
	ds_write_b32 v226, v220
	v_add_u32_e32 v227, v151, v169
	ds_write_b32 v227, v221
	v_add_u32_e32 v226, v151, v170
	ds_write_b32 v226, v2
	v_add_u32_e32 v227, v151, v171
	ds_write_b32 v227, v3
	v_add_u32_e32 v226, v151, v172
	ds_write_b32 v226, v4
	v_add_u32_e32 v227, v151, v173
	ds_write_b32 v227, v5
	v_add_u32_e32 v226, v151, v174
	ds_write_b32 v226, v6
	v_add_u32_e32 v227, v151, v175
	ds_write_b32 v227, v7
	v_add_u32_e32 v226, v151, v176
	ds_write_b32 v226, v8
	v_add_u32_e32 v227, v151, v177
	ds_write_b32 v227, v9
